# x14: as x12 plus K-fragment prefetch in both bodies QK phases, group B runs QK before PV
# baseline (speedup 1.0000x reference)
; #define SBAR() __builtin_amdgcn_sched_barrier(0)
; #define SLOAD(i, j) do { const long kr_ = KROW(j); sr_[i].vs0 = ld8(Vp + (kr_ + sr) * ldv + sc); sr_[i].ks0 = ld8(Kp + (kr_ + sr) * ldk + sc); \
;     if (DQK == 96) sr_[i].ks1 = ld8(Kp + (kr_ + sr2) * ldk + sc2); } while (0)
; __device__ __forceinline__ void finishSM(f32x16& p0, f32x16& p1, float alpha, float& l_reg, bf16x8& pa0, bf16x8& pa1, bf16x8& pa2, bf16x8& pa3) {
; #pragma unroll
;   for (int r = 0; r < 16; ++r) p1[r] = __builtin_amdgcn_exp2f(p1[r]);
;   float ps = 0;
; #pragma unroll
;   for (int r = 0; r < 16; ++r) ps += p0[r];
; #pragma unroll
;   for (int r = 0; r < 16; ++r) ps += p1[r];
;   { auto rr = __builtin_amdgcn_permlane32_swap(__float_as_uint(ps), __float_as_uint(ps), false, false);
;     ps = __uint_as_float(rr[0]) + __uint_as_float(rr[1]); }
;   l_reg = l_reg * alpha + ps;
;     ...
;   PK4(p0, 0, pa0); PK4(p0, 8, pa1); PK4(p1, 0, pa2); PK4(p1, 8, pa3);
;     ...
; }
; template <int DQK> __device__ __forceinline__ void qkt(f32x16& p0, f32x16& p1, const char* Ks, const bf16x8* qr, int r32, int hi) {
;   p0 = f32x16{}; p1 = f32x16{};
; #pragma unroll
;   for (int d0 = 0; d0 < DQK / 16; ++d0) { int cb = (d0 * 16 + hi * 8) * 2;
;     bf16x8 b0 = *reinterpret_cast<const bf16x8*>(Ks + KSWZ(r32, cb));
;     bf16x8 b1 = *reinterpret_cast<const bf16x8*>(Ks + KSWZ(32 + r32, cb));
;     p0 = __builtin_amdgcn_mfma_f32_32x32x16_bf16(b0, qr[d0], p0, 0, 0, 0);
;     p1 = __builtin_amdgcn_mfma_f32_32x32x16_bf16(b1, qr[d0], p1, 0, 0, 0); }
; }
; template <int DQK, int MODE, int ldq, int ldk, int ldv> ...
;     ...
;   for (int j = 1; j + 1 < NT; j += 2) {
;     SBAR(); qkt<DQK>(pB0, pB1, K_lds + SHM_K, qr, r32, hi);
;     finishSM(pA0, pA1, alA, l_reg, pa0, pa1, pa2, pa3); SBAR();
;     SLOAD(SO, j + 2); SBAR();
.LBB0_300:
	s_add_i32 s25, s11, -3
	s_cmp_lg_u32 s32, 0
	s_cbranch_scc1 .Lmy_h1B
	ds_read_b128 v[32:35], v148 offset:49152
	ds_read_b128 v[36:39], v148 offset:57344
	ds_read_b128 v[164:167], v152 offset:49152
	ds_read_b128 v[168:171], v152 offset:57344
	ds_read_b128 v[184:187], v151 offset:49152
	ds_read_b128 v[188:191], v151 offset:57344
	s_waitcnt lgkmcnt(5)
	v_mfma_f32_32x32x16_bf16 v[48:63], v[32:35], v[84:87], 0
	s_waitcnt lgkmcnt(4)
	v_mfma_f32_32x32x16_bf16 v[32:47], v[36:39], v[84:87], 0
	s_waitcnt lgkmcnt(3)
	v_mfma_f32_32x32x16_bf16 v[48:63], v[164:167], v[80:83], v[48:63]
	s_waitcnt lgkmcnt(2)
	v_mfma_f32_32x32x16_bf16 v[32:47], v[168:171], v[80:83], v[32:47]
	ds_read_b128 v[164:167], v149 offset:49152
	ds_read_b128 v[168:171], v149 offset:57344
	s_waitcnt lgkmcnt(3)
	v_mfma_f32_32x32x16_bf16 v[48:63], v[184:187], v[76:79], v[48:63]
	s_waitcnt lgkmcnt(2)
	v_mfma_f32_32x32x16_bf16 v[32:47], v[188:191], v[76:79], v[32:47]
	ds_read_b128 v[184:187], v150 offset:49152
	ds_read_b128 v[188:191], v150 offset:57344
	s_waitcnt lgkmcnt(3)
	v_mfma_f32_32x32x16_bf16 v[48:63], v[164:167], v[72:75], v[48:63]
	s_waitcnt lgkmcnt(2)
	v_mfma_f32_32x32x16_bf16 v[32:47], v[168:171], v[72:75], v[32:47]
	ds_read_b128 v[164:167], v153 offset:49152
	ds_read_b128 v[168:171], v153 offset:57344
	s_waitcnt lgkmcnt(3)
	v_mfma_f32_32x32x16_bf16 v[48:63], v[184:187], v[68:71], v[48:63]
	s_waitcnt lgkmcnt(2)
	v_mfma_f32_32x32x16_bf16 v[32:47], v[188:191], v[68:71], v[32:47]
	s_waitcnt vmcnt(0)
	ds_write_b128 v146, v[88:91] offset:32768
	ds_write_b128 v147, v[96:99] offset:32768
	ds_write_b128 v145, v[92:95] offset:16384
	s_waitcnt lgkmcnt(4)
	v_mfma_f32_32x32x16_bf16 v[48:63], v[164:167], v[64:67], v[48:63]
	s_waitcnt lgkmcnt(3)
	v_mfma_f32_32x32x16_bf16 v[32:47], v[168:171], v[64:67], v[32:47]
	ds_read_b64_tr_b16 v[192:193], v144 offset:0
	ds_read_b64_tr_b16 v[194:195], v144 offset:0x800
	ds_read_b64_tr_b16 v[196:197], v144 offset:0x1000
	ds_read_b64_tr_b16 v[198:199], v144 offset:0x1800
	ds_read_b64_tr_b16 v[200:201], v144 offset:0x2000
	ds_read_b64_tr_b16 v[202:203], v144 offset:0x2800
	ds_read_b64_tr_b16 v[210:211], v144 offset:0x3000
	ds_read_b64_tr_b16 v[212:213], v144 offset:0x3800
	v_exp_f32_e32 v117, v114
	v_exp_f32_e32 v157, v115
	v_exp_f32_e32 v108, v108
	v_exp_f32_e32 v109, v109
	v_exp_f32_e32 v104, v104
	v_exp_f32_e32 v105, v105
	v_exp_f32_e32 v102, v102
	v_exp_f32_e32 v103, v103
	v_exp_f32_e32 v110, v110
	v_exp_f32_e32 v111, v111
	v_exp_f32_e32 v106, v106
	v_exp_f32_e32 v107, v107
	v_exp_f32_e32 v100, v100
	v_exp_f32_e32 v101, v101
	v_exp_f32_e32 v164, v112
	v_add_f32_e32 v112, 0, v126
	v_add_f32_e32 v112, v160, v112
	v_add_f32_e32 v112, v127, v112
	v_add_f32_e32 v112, v161, v112
	v_add_f32_e32 v112, v158, v112
	v_add_f32_e32 v112, v162, v112
	v_add_f32_e32 v112, v159, v112
	v_add_f32_e32 v112, v163, v112
	v_add_f32_e32 v112, v118, v112
	v_add_f32_e32 v112, v121, v112
	v_add_f32_e32 v112, v119, v112
	v_add_f32_e32 v112, v122, v112
	v_add_f32_e32 v112, v120, v112
	v_add_f32_e32 v112, v123, v112
	v_add_f32_e32 v112, v124, v112
	v_exp_f32_e32 v165, v113
	v_add_f32_e32 v112, v125, v112
	v_add_f32_e32 v112, v117, v112
	v_add_f32_e32 v112, v157, v112
	v_add_f32_e32 v112, v164, v112
	v_add_f32_e32 v112, v165, v112
	v_add_f32_e32 v112, v108, v112
	v_add_f32_e32 v112, v109, v112
	v_add_f32_e32 v112, v104, v112
	v_add_f32_e32 v112, v105, v112
	v_add_f32_e32 v112, v102, v112
	v_add_f32_e32 v112, v103, v112
	v_add_f32_e32 v112, v110, v112
	v_add_f32_e32 v112, v111, v112
	v_add_f32_e32 v112, v106, v112
	v_add_f32_e32 v112, v107, v112
	v_add_f32_e32 v112, v100, v112
	v_add_f32_e32 v155, v101, v112
	v_mov_b32_e32 v156, v155
	v_cvt_pk_bf16_f32 v214, v126, v160
	v_cvt_pk_bf16_f32 v215, v127, v161
	v_cvt_pk_bf16_f32 v216, v158, v162
	s_nop 1
	v_permlane32_swap_b32_e32 v155, v156
	v_cvt_pk_bf16_f32 v217, v159, v163
	v_permlane32_swap_b32_e32 v214, v216
	v_cvt_pk_bf16_f32 v218, v118, v121
	v_cvt_pk_bf16_f32 v219, v119, v122
	v_cvt_pk_bf16_f32 v220, v120, v123
	v_cvt_pk_bf16_f32 v221, v124, v125
	v_cvt_pk_bf16_f32 v222, v117, v157
	v_cvt_pk_bf16_f32 v223, v164, v165
	v_cvt_pk_bf16_f32 v224, v108, v109
	v_cvt_pk_bf16_f32 v225, v104, v105
	v_cvt_pk_bf16_f32 v226, v102, v103
	v_cvt_pk_bf16_f32 v227, v110, v111
	v_cvt_pk_bf16_f32 v228, v106, v107
	v_cvt_pk_bf16_f32 v229, v100, v101
	v_permlane32_swap_b32_e32 v215, v217
	v_permlane32_swap_b32_e32 v218, v220
	v_permlane32_swap_b32_e32 v219, v221
	v_permlane32_swap_b32_e32 v222, v224
	v_permlane32_swap_b32_e32 v223, v225
	v_permlane32_swap_b32_e32 v226, v228
	v_permlane32_swap_b32_e32 v227, v229
	s_cmpk_lt_u32 s25, 0x7e
	s_cselect_b32 s0, 0, 0xffffff80
	s_cselect_b32 s1, s10, s24
	s_add_i32 s0, s0, s11
	s_lshl_b32 s0, s0, 6
	s_add_i32 s0, s0, s1
	s_sub_i32 s0, s0, 64
	s_ashr_i32 s1, s0, 31
	s_cmpk_lt_u32 s25, 0x7f
	s_cselect_b32 s98, 0, 0xffffff80
	s_cselect_b32 s99, s10, s24
	s_add_i32 s98, s98, s11
	s_lshl_b32 s98, s98, 6
	s_add_i32 s98, s98, s99
	s_addk_i32 s98, 0xff80
	s_ashr_i32 s99, s98, 31
	v_lshl_add_u64 v[100:101], s[0:1], 0, v[130:131]
	v_lshl_add_u64 v[104:105], s[98:99], 0, v[130:131]
	v_lshlrev_b64 v[104:105], 9, v[104:105]
	v_lshl_add_u64 v[104:105], v[134:135], 0, v[104:105]
	v_mad_u64_u32 v[102:103], s[12:13], v100, s70, v[136:137]
	v_or_b32_e32 v106, s0, v132
	v_mad_i32_i24 v103, v101, s70, v103
	v_mad_i64_i32 v[106:107], s[0:1], v106, s70, v[138:139]
	global_load_dwordx4 v[100:103], v[102:103], off
	s_nop 0
	global_load_dwordx4 v[108:111], v[104:105], off
	s_nop 0
	global_load_dwordx4 v[104:107], v[106:107], off offset:128
	s_waitcnt lgkmcnt(0)
; #define SBAR() __builtin_amdgcn_sched_barrier(0)
; template <int DQK> __device__ __forceinline__ void partialSM(f32x16& p0, f32x16& p1, float& m_reg, float& mn, float& alpha) {
;   constexpr float SCALE = (DQK == 96) ? 0.10206207261596577f : 0.125f;
;   constexpr float C = SCALE * 1.4426950408889634f;
;   float pmax = p0[0];
; #pragma unroll
;   for (int r = 1; r < 16; ++r) pmax = fmaxf(pmax, p0[r]);
; #pragma unroll
;   for (int r = 0; r < 16; ++r) pmax = fmaxf(pmax, p1[r]);
;   { auto rr = __builtin_amdgcn_permlane32_swap(__float_as_uint(pmax), __float_as_uint(pmax), false, false);
;     pmax = fmaxf(__uint_as_float(rr[0]), __uint_as_float(rr[1])); }
;   if (__builtin_expect(__all(pmax - m_reg <= THR / SCALE), 1)) { mn = m_reg; alpha = 1.f; }
;   else { mn = fmaxf(m_reg, pmax); alpha = __builtin_amdgcn_exp2f((m_reg - mn) * C); m_reg = mn; }
;   float mnC = -mn * C;
; #pragma unroll
;   for (int r = 0; r < 16; ++r) p0[r] = fmaf(p0[r], C, mnC);
; #pragma unroll
;   for (int r = 0; r < 16; ++r) p1[r] = fmaf(p1[r], C, mnC);
; #pragma unroll
;   for (int r = 0; r < 16; ++r) p0[r] = __builtin_amdgcn_exp2f(p0[r]);
; }
; template <int D0> __device__ __forceinline__ void pv_one(f32x16& od, int vb, bf16x8 pa0, bf16x8 pa1, bf16x8 pa2, bf16x8 pa3) {
;   const s16x4 l0 = tr_read<v_rd_off(D0, 0, 0)>(vb), h0 = tr_read<v_rd_off(D0, 0, 1)>(vb), l1 = tr_read<v_rd_off(D0, 1, 0)>(vb), h1 = tr_read<v_rd_off(D0, 1, 1)>(vb);
;   const s16x4 l2 = tr_read<v_rd_off(D0, 2, 0)>(vb), h2 = tr_read<v_rd_off(D0, 2, 1)>(vb), l3 = tr_read<v_rd_off(D0, 3, 0)>(vb), h3 = tr_read<v_rd_off(D0, 3, 1)>(vb);
;   asm volatile("s_waitcnt lgkmcnt(0)" ::: "memory"); SBAR();
;   od = __builtin_amdgcn_mfma_f32_32x32x16_bf16(pa0, PKLH(l0, h0), od, 0, 0, 0);
;   od = __builtin_amdgcn_mfma_f32_32x32x16_bf16(pa1, PKLH(l1, h1), od, 0, 0, 0);
;   od = __builtin_amdgcn_mfma_f32_32x32x16_bf16(pa2, PKLH(l2, h2), od, 0, 0, 0);
;   od = __builtin_amdgcn_mfma_f32_32x32x16_bf16(pa3, PKLH(l3, h3), od, 0, 0, 0);
; }
; __device__ __forceinline__ void pv_d0(f32x16* o, int vb, bf16x8 pa0, bf16x8 pa1, bf16x8 pa2, bf16x8 pa3) {
;   pv_one<0>(o[0], vb, pa0, pa1, pa2, pa3); pv_one<1>(o[1], vb, pa0, pa1, pa2, pa3);
; }
	s_nop 0
	v_mfma_f32_32x32x16_bf16 v[0:15], v[214:217], v[192:195], v[0:15]
	ds_read_b64_tr_b16 v[192:193], v144 offset:0x200
	ds_read_b64_tr_b16 v[194:195], v144 offset:0xa00
	v_max_f32_e32 v112, v48, v49
	v_max3_f32 v112, v112, v50, v51
	v_max3_f32 v112, v112, v52, v53
	v_max3_f32 v112, v112, v54, v55
	v_max3_f32 v112, v112, v56, v57
	v_max3_f32 v112, v112, v58, v59
	v_max3_f32 v112, v112, v60, v61
	v_max3_f32 v112, v112, v62, v63
	v_mfma_f32_32x32x16_bf16 v[0:15], v[218:221], v[196:199], v[0:15]
	ds_read_b64_tr_b16 v[196:197], v144 offset:0x1200
	ds_read_b64_tr_b16 v[198:199], v144 offset:0x1a00
	v_max3_f32 v112, v112, v32, v33
	v_max3_f32 v112, v112, v34, v35
	v_max3_f32 v112, v112, v36, v37
	v_max3_f32 v112, v112, v38, v39
	v_max3_f32 v112, v112, v40, v41
	v_max3_f32 v112, v112, v42, v43
	v_max3_f32 v112, v112, v44, v45
	v_max3_f32 v112, v112, v46, v47
	v_mfma_f32_32x32x16_bf16 v[0:15], v[222:225], v[200:203], v[0:15]
	ds_read_b64_tr_b16 v[200:201], v144 offset:0x2200
	ds_read_b64_tr_b16 v[202:203], v144 offset:0x2a00
	v_mov_b32_e32 v113, v112
	s_nop 1
	v_permlane32_swap_b32_e32 v112, v113
	v_max_f32_e32 v112, v112, v113
	v_sub_f32_e32 v113, v112, v116
	v_cmp_ge_f32_e32 vcc, s80, v113
	v_max_f32_e32 v112, v116, v112
	v_sub_f32_e32 v113, v116, v112
	v_mfma_f32_32x32x16_bf16 v[0:15], v[226:229], v[210:213], v[0:15]
	ds_read_b64_tr_b16 v[210:211], v144 offset:0x3200
	ds_read_b64_tr_b16 v[212:213], v144 offset:0x3a00
	v_mul_f32_e32 v113, 0x3e16c740, v113
	v_exp_f32_e32 v113, v113
	s_cmp_eq_u64 vcc, exec
	s_cselect_b64 s[0:1], -1, 0
	v_cndmask_b32_e64 v157, v113, 1.0, s[0:1]
	v_cmp_gt_f32_e32 vcc, 1.0, v157
	s_waitcnt lgkmcnt(0)
	v_mfma_f32_32x32x16_bf16 v[16:31], v[214:217], v[192:195], v[16:31]
	v_cndmask_b32_e64 v158, v112, v116, s[0:1]
	v_mul_f32_e32 v159, 0xbe16c740, v158
	v_fmamk_f32 v48, v48, 0x3e16c740, v159
	v_fmamk_f32 v49, v49, 0x3e16c740, v159
	v_fmamk_f32 v50, v50, 0x3e16c740, v159
	v_fmamk_f32 v51, v51, 0x3e16c740, v159
	v_fmamk_f32 v52, v52, 0x3e16c740, v159
	v_fmamk_f32 v53, v53, 0x3e16c740, v159
	v_fmamk_f32 v54, v54, 0x3e16c740, v159
	v_fmamk_f32 v55, v55, 0x3e16c740, v159
	v_fmamk_f32 v56, v56, 0x3e16c740, v159
	v_fmamk_f32 v57, v57, 0x3e16c740, v159
	v_fmamk_f32 v58, v58, 0x3e16c740, v159
	v_mfma_f32_32x32x16_bf16 v[16:31], v[218:221], v[196:199], v[16:31]
	v_fmamk_f32 v59, v59, 0x3e16c740, v159
	v_fmamk_f32 v60, v60, 0x3e16c740, v159
	v_fmamk_f32 v61, v61, 0x3e16c740, v159
	v_fmamk_f32 v62, v62, 0x3e16c740, v159
	v_fmamk_f32 v63, v63, 0x3e16c740, v159
	v_exp_f32_e32 v112, v48
	v_exp_f32_e32 v127, v49
	v_exp_f32_e32 v113, v50
	v_exp_f32_e32 v126, v51
	v_exp_f32_e32 v114, v52
	v_exp_f32_e32 v125, v53
	v_exp_f32_e32 v115, v54
	v_exp_f32_e32 v124, v55
	v_mfma_f32_32x32x16_bf16 v[16:31], v[222:225], v[200:203], v[16:31]
	v_exp_f32_e32 v116, v56
	v_exp_f32_e32 v123, v57
	v_exp_f32_e32 v117, v58
	v_exp_f32_e32 v122, v59
	v_exp_f32_e32 v118, v60
	v_exp_f32_e32 v121, v61
	v_exp_f32_e32 v119, v62
	v_exp_f32_e32 v120, v63
	v_fmamk_f32 v164, v42, 0x3e16c740, v159
	v_fmamk_f32 v165, v43, 0x3e16c740, v159
	v_fmamk_f32 v167, v32, 0x3e16c740, v159
	v_fmamk_f32 v168, v33, 0x3e16c740, v159
	v_fmamk_f32 v169, v34, 0x3e16c740, v159
	v_mfma_f32_32x32x16_bf16 v[16:31], v[226:229], v[210:213], v[16:31]
	v_fmamk_f32 v170, v35, 0x3e16c740, v159
	v_fmamk_f32 v171, v36, 0x3e16c740, v159
	v_fmamk_f32 v172, v37, 0x3e16c740, v159
	v_fmamk_f32 v160, v38, 0x3e16c740, v159
	v_fmamk_f32 v161, v39, 0x3e16c740, v159
	v_fmamk_f32 v162, v40, 0x3e16c740, v159
	v_fmamk_f32 v163, v41, 0x3e16c740, v159
	v_fmamk_f32 v166, v44, 0x3e16c740, v159
	v_fmamk_f32 v173, v45, 0x3e16c740, v159
	v_fmamk_f32 v174, v46, 0x3e16c740, v159
	v_fmac_f32_e32 v159, 0x3e16c740, v47
	s_cbranch_vccz .LBB0_304
	s_and_saveexec_b64 s[12:13], s[4:5]
	ds_write_b32 v141, v157 offset:128
	s_or_b64 exec, exec, s[12:13]
	s_waitcnt lgkmcnt(0)
	ds_read_b128 v[192:195], v129 offset:224
	ds_read_b128 v[196:199], v129 offset:192
	ds_read_b128 v[200:203], v129 offset:160
	ds_read_b128 v[210:213], v129 offset:128
	s_waitcnt lgkmcnt(3)
	v_pk_mul_f32 v[14:15], v[14:15], v[194:195]
	s_waitcnt lgkmcnt(2)
	v_pk_mul_f32 v[10:11], v[10:11], v[198:199]
	s_waitcnt lgkmcnt(1)
	v_pk_mul_f32 v[6:7], v[6:7], v[202:203]
	s_waitcnt lgkmcnt(0)
	v_pk_mul_f32 v[2:3], v[2:3], v[212:213]
	v_pk_mul_f32 v[12:13], v[12:13], v[192:193]
	v_pk_mul_f32 v[8:9], v[8:9], v[196:197]
	v_pk_mul_f32 v[4:5], v[4:5], v[200:201]
	v_pk_mul_f32 v[0:1], v[0:1], v[210:211]
	v_pk_mul_f32 v[30:31], v[30:31], v[194:195]
	v_pk_mul_f32 v[26:27], v[26:27], v[198:199]
	v_pk_mul_f32 v[22:23], v[22:23], v[202:203]
	v_pk_mul_f32 v[18:19], v[18:19], v[212:213]
	v_pk_mul_f32 v[28:29], v[28:29], v[192:193]
	v_pk_mul_f32 v[24:25], v[24:25], v[196:197]
	v_pk_mul_f32 v[20:21], v[20:21], v[200:201]
	v_pk_mul_f32 v[16:17], v[16:17], v[210:211]
; #define SBAR() __builtin_amdgcn_sched_barrier(0)
; #define SLOAD(i, j) do { const long kr_ = KROW(j); sr_[i].vs0 = ld8(Vp + (kr_ + sr) * ldv + sc); sr_[i].ks0 = ld8(Kp + (kr_ + sr) * ldk + sc); \
;     if (DQK == 96) sr_[i].ks1 = ld8(Kp + (kr_ + sr2) * ldk + sc2); } while (0)
; #define SWRITE(b, i) do { *(bf16x8*)(V_lds + (b) * SHM_V + vst0) = sr_[i].vs0; *(bf16x8*)(K_lds + (b) * SHM_K + kst0) = sr_[i].ks0; \
;     if (DQK == 96) *(bf16x8*)(K_lds + (b) * SHM_K + kst1) = sr_[i].ks1; } while (0)
; #define RESC(a) do { if (__any((a) < 1.f)) { if (hi == 0) al_l[r32] = (a); asm volatile("s_waitcnt lgkmcnt(0)" ::: "memory"); \
;     _Pragma("unroll") for (int d = 0; d < 2; ++d) _Pragma("unroll") for (int r = 0; r < 16; ++r) o[d][r] *= al_l[crow(r, hi)]; } } while (0)
; __device__ __forceinline__ void finishSM(f32x16& p0, f32x16& p1, float alpha, float& l_reg, bf16x8& pa0, bf16x8& pa1, bf16x8& pa2, bf16x8& pa3) {
; #pragma unroll
;   for (int r = 0; r < 16; ++r) p1[r] = __builtin_amdgcn_exp2f(p1[r]);
;   float ps = 0;
; #pragma unroll
;   for (int r = 0; r < 16; ++r) ps += p0[r];
; #pragma unroll
;   for (int r = 0; r < 16; ++r) ps += p1[r];
;   { auto rr = __builtin_amdgcn_permlane32_swap(__float_as_uint(ps), __float_as_uint(ps), false, false);
;     ps = __uint_as_float(rr[0]) + __uint_as_float(rr[1]); }
;   l_reg = l_reg * alpha + ps;
;     ...
;   PK4(p0, 0, pa0); PK4(p0, 8, pa1); PK4(p1, 0, pa2); PK4(p1, 8, pa3);
;     ...
; }
; template <int DQK> __device__ __forceinline__ void qkt(f32x16& p0, f32x16& p1, const char* Ks, const bf16x8* qr, int r32, int hi) {
;   p0 = f32x16{}; p1 = f32x16{};
; #pragma unroll
;   for (int d0 = 0; d0 < DQK / 16; ++d0) { int cb = (d0 * 16 + hi * 8) * 2;
;     bf16x8 b0 = *reinterpret_cast<const bf16x8*>(Ks + KSWZ(r32, cb));
;     bf16x8 b1 = *reinterpret_cast<const bf16x8*>(Ks + KSWZ(32 + r32, cb));
;     p0 = __builtin_amdgcn_mfma_f32_32x32x16_bf16(b0, qr[d0], p0, 0, 0, 0);
;     p1 = __builtin_amdgcn_mfma_f32_32x32x16_bf16(b1, qr[d0], p1, 0, 0, 0); }
; }
; template <int DQK, int MODE, int ldq, int ldk, int ldv> ...
;     ...
;     __syncthreads(); SWRITE(0, SE);
;     RESC(alB); __syncthreads();
;     SBAR(); qkt<DQK>(pA0, pA1, K_lds, qr, r32, hi);
;     finishSM(pB0, pB1, alB, l_reg, pa0, pa1, pa2, pa3); SBAR();
;     if (j + 3 < NT) SLOAD(SE, j + 3); SBAR();
.LBB0_304:
	s_waitcnt lgkmcnt(0)
	s_barrier
	ds_read_b128 v[32:35], v148 offset:32768
	ds_read_b128 v[36:39], v148 offset:40960
	ds_read_b128 v[176:179], v152 offset:32768
	ds_read_b128 v[180:183], v152 offset:40960
	ds_read_b128 v[184:187], v151 offset:32768
	ds_read_b128 v[188:191], v151 offset:40960
	s_waitcnt lgkmcnt(5)
	v_mfma_f32_32x32x16_bf16 v[48:63], v[32:35], v[84:87], 0
	s_waitcnt lgkmcnt(4)
	v_mfma_f32_32x32x16_bf16 v[32:47], v[36:39], v[84:87], 0
	s_waitcnt lgkmcnt(3)
	v_mfma_f32_32x32x16_bf16 v[48:63], v[176:179], v[80:83], v[48:63]
	s_waitcnt lgkmcnt(2)
	v_mfma_f32_32x32x16_bf16 v[32:47], v[180:183], v[80:83], v[32:47]
	ds_read_b128 v[176:179], v149 offset:32768
	ds_read_b128 v[180:183], v149 offset:40960
	s_waitcnt lgkmcnt(3)
	v_mfma_f32_32x32x16_bf16 v[48:63], v[184:187], v[76:79], v[48:63]
	s_waitcnt lgkmcnt(2)
	v_mfma_f32_32x32x16_bf16 v[32:47], v[188:191], v[76:79], v[32:47]
	ds_read_b128 v[184:187], v150 offset:32768
	ds_read_b128 v[188:191], v150 offset:40960
	s_waitcnt lgkmcnt(3)
	v_mfma_f32_32x32x16_bf16 v[48:63], v[176:179], v[72:75], v[48:63]
	s_waitcnt lgkmcnt(2)
	v_mfma_f32_32x32x16_bf16 v[32:47], v[180:183], v[72:75], v[32:47]
	ds_read_b128 v[176:179], v153 offset:32768
	ds_read_b128 v[180:183], v153 offset:40960
	s_waitcnt lgkmcnt(3)
	v_mfma_f32_32x32x16_bf16 v[48:63], v[184:187], v[68:71], v[48:63]
	s_waitcnt lgkmcnt(2)
	v_mfma_f32_32x32x16_bf16 v[32:47], v[188:191], v[68:71], v[32:47]
	s_waitcnt vmcnt(0)
	ds_write_b128 v146, v[100:103] offset:49152
	ds_write_b128 v147, v[104:107] offset:49152
	ds_write_b128 v145, v[108:111]
	s_waitcnt lgkmcnt(4)
	v_mfma_f32_32x32x16_bf16 v[48:63], v[176:179], v[64:67], v[48:63]
	s_waitcnt lgkmcnt(3)
	v_mfma_f32_32x32x16_bf16 v[32:47], v[180:183], v[64:67], v[32:47]
	ds_read_b64_tr_b16 v[192:193], v143 offset:0
	ds_read_b64_tr_b16 v[194:195], v143 offset:0x800
	ds_read_b64_tr_b16 v[196:197], v143 offset:0x1000
	ds_read_b64_tr_b16 v[198:199], v143 offset:0x1800
	ds_read_b64_tr_b16 v[200:201], v143 offset:0x2000
	ds_read_b64_tr_b16 v[202:203], v143 offset:0x2800
	ds_read_b64_tr_b16 v[210:211], v143 offset:0x3000
	ds_read_b64_tr_b16 v[212:213], v143 offset:0x3800
	v_exp_f32_e32 v175, v164
	v_add_f32_e32 v164, 0, v112
	v_add_f32_e32 v164, v127, v164
	v_add_f32_e32 v164, v113, v164
	v_add_f32_e32 v164, v126, v164
	v_add_f32_e32 v164, v114, v164
	v_add_f32_e32 v164, v125, v164
	v_add_f32_e32 v164, v115, v164
	v_add_f32_e32 v164, v124, v164
	v_add_f32_e32 v164, v116, v164
	v_add_f32_e32 v164, v123, v164
	v_add_f32_e32 v164, v117, v164
	v_add_f32_e32 v164, v122, v164
	v_exp_f32_e32 v167, v167
	v_add_f32_e32 v164, v118, v164
	v_exp_f32_e32 v168, v168
	v_add_f32_e32 v164, v121, v164
	v_exp_f32_e32 v169, v169
	v_add_f32_e32 v164, v119, v164
	v_exp_f32_e32 v170, v170
	v_add_f32_e32 v164, v120, v164
	v_exp_f32_e32 v171, v171
	v_add_f32_e32 v164, v167, v164
	v_exp_f32_e32 v172, v172
	v_add_f32_e32 v164, v168, v164
	v_exp_f32_e32 v160, v160
	v_add_f32_e32 v164, v169, v164
	v_exp_f32_e32 v161, v161
	v_add_f32_e32 v164, v170, v164
	v_exp_f32_e32 v162, v162
	v_add_f32_e32 v164, v171, v164
	v_exp_f32_e32 v163, v163
	v_add_f32_e32 v164, v172, v164
	v_add_f32_e32 v164, v160, v164
	v_add_f32_e32 v164, v161, v164
	v_exp_f32_e32 v166, v166
	v_add_f32_e32 v164, v162, v164
	v_exp_f32_e32 v173, v173
	v_add_f32_e32 v164, v163, v164
	v_exp_f32_e32 v174, v174
	v_add_f32_e32 v164, v175, v164
	v_exp_f32_e32 v159, v159
	v_cvt_pk_bf16_f32 v214, v112, v127
	v_cvt_pk_bf16_f32 v215, v113, v126
	v_cvt_pk_bf16_f32 v216, v114, v125
	v_cvt_pk_bf16_f32 v217, v115, v124
	v_cvt_pk_bf16_f32 v218, v116, v123
	v_cvt_pk_bf16_f32 v219, v117, v122
	v_exp_f32_e32 v176, v165
	v_cvt_pk_bf16_f32 v220, v118, v121
	v_cvt_pk_bf16_f32 v221, v119, v120
	v_cvt_pk_bf16_f32 v222, v167, v168
	v_cvt_pk_bf16_f32 v223, v169, v170
	v_cvt_pk_bf16_f32 v224, v171, v172
	s_nop 0
	v_add_f32_e32 v164, v176, v164
	v_add_f32_e32 v164, v166, v164
	v_add_f32_e32 v164, v173, v164
	v_add_f32_e32 v164, v174, v164
	v_add_f32_e32 v164, v159, v164
	v_mov_b32_e32 v165, v164
	v_cvt_pk_bf16_f32 v225, v160, v161
	v_cvt_pk_bf16_f32 v226, v162, v163
	v_cvt_pk_bf16_f32 v227, v175, v176
	v_cvt_pk_bf16_f32 v228, v166, v173
	v_cvt_pk_bf16_f32 v229, v174, v159
	s_nop 1
	v_permlane32_swap_b32_e32 v164, v165
	v_permlane32_swap_b32_e32 v214, v216
	v_permlane32_swap_b32_e32 v215, v217
	v_permlane32_swap_b32_e32 v218, v220
	v_permlane32_swap_b32_e32 v219, v221
	v_permlane32_swap_b32_e32 v222, v224
	v_permlane32_swap_b32_e32 v223, v225
	v_permlane32_swap_b32_e32 v226, v228
	v_permlane32_swap_b32_e32 v227, v229
	s_cmpk_lt_u32 s25, 0x7e
	s_cselect_b32 s98, 0, 0xffffff80
	s_cselect_b32 s99, s10, s24
	s_add_i32 s98, s98, s11
	s_lshl_b32 s98, s98, 6
	s_add_i32 s98, s98, s99
	s_sub_i32 s98, s98, 64
	s_ashr_i32 s99, s98, 31
	v_lshl_add_u64 v[92:93], s[98:99], 0, v[130:131]
	v_lshlrev_b64 v[92:93], 9, v[92:93]
	v_lshl_add_u64 v[92:93], v[134:135], 0, v[92:93]
	global_load_dwordx4 v[92:95], v[92:93], off
	s_cmpk_gt_u32 s25, 0x80
	s_cbranch_scc1 .LBB0_306
	s_cmpk_lt_u32 s25, 0x7d
	s_cselect_b32 s0, 0, 0xffffff80
	s_cselect_b32 s1, s10, s24
	s_add_i32 s0, s0, s11
	s_lshl_b32 s0, s0, 6
	s_add_i32 s0, s0, s1
	s_ashr_i32 s1, s0, 31
	v_lshl_add_u64 v[88:89], s[0:1], 0, v[130:131]
	v_mad_u64_u32 v[90:91], s[12:13], v88, s70, v[136:137]
	v_or_b32_e32 v96, s0, v132
	v_mad_i32_i24 v91, v89, s70, v91
	v_mad_i64_i32 v[96:97], s[0:1], v96, s70, v[138:139]
	global_load_dwordx4 v[88:91], v[90:91], off
	s_nop 0
	s_nop 0
	global_load_dwordx4 v[96:99], v[96:97], off offset:128

; #define SBAR() __builtin_amdgcn_sched_barrier(0)
; #define SLOAD(i, j) do { const long kr_ = KROW(j); sr_[i].vs0 = ld8(Vp + (kr_ + sr) * ldv + sc); sr_[i].ks0 = ld8(Kp + (kr_ + sr) * ldk + sc); \
;     if (DQK == 96) sr_[i].ks1 = ld8(Kp + (kr_ + sr2) * ldk + sc2); } while (0)
; #define BIAS(P0, P1, j) do { if (MODE == 1) { SBAR(); if ((j) >= nA) na_bias(P0, P1, na, rs0 + (j) - nA, hi); SBAR(); } } while (0)
; __device__ __forceinline__ void finishSM(f32x16& p0, f32x16& p1, float alpha, float& l_reg, bf16x8& pa0, bf16x8& pa1, bf16x8& pa2, bf16x8& pa3) {
; #pragma unroll
;   for (int r = 0; r < 16; ++r) p1[r] = __builtin_amdgcn_exp2f(p1[r]);
;   float ps = 0;
; #pragma unroll
;   for (int r = 0; r < 16; ++r) ps += p0[r];
; #pragma unroll
;   for (int r = 0; r < 16; ++r) ps += p1[r];
;   { auto rr = __builtin_amdgcn_permlane32_swap(__float_as_uint(ps), __float_as_uint(ps), false, false);
;     ps = __uint_as_float(rr[0]) + __uint_as_float(rr[1]); }
;   l_reg = l_reg * alpha + ps;
;     ...
;   PK4(p0, 0, pa0); PK4(p0, 8, pa1); PK4(p1, 0, pa2); PK4(p1, 8, pa3);
;     ...
; }
; template <int DQK> __device__ __forceinline__ void qkt(f32x16& p0, f32x16& p1, const char* Ks, const bf16x8* qr, int r32, int hi) {
;   p0 = f32x16{}; p1 = f32x16{};
; #pragma unroll
;   for (int d0 = 0; d0 < DQK / 16; ++d0) { int cb = (d0 * 16 + hi * 8) * 2;
;     bf16x8 b0 = *reinterpret_cast<const bf16x8*>(Ks + KSWZ(r32, cb));
;     bf16x8 b1 = *reinterpret_cast<const bf16x8*>(Ks + KSWZ(32 + r32, cb));
;     p0 = __builtin_amdgcn_mfma_f32_32x32x16_bf16(b0, qr[d0], p0, 0, 0, 0);
;     p1 = __builtin_amdgcn_mfma_f32_32x32x16_bf16(b1, qr[d0], p1, 0, 0, 0); }
; }
; template <int DQK, int MODE, int ldq, int ldk, int ldv> ...
;     ...
;   for (int j = 1; j + 1 < NT; j += 2) {
;     SBAR(); qkt<DQK>(pB0, pB1, K_lds + SHM_K, qr, r32, hi);
;     finishSM(pA0, pA1, alA, l_reg, pa0, pa1, pa2, pa3); SBAR();
;     SLOAD(SO, j + 2); SBAR();
;     pv_d0(o, vb0, pa0, pa1, pa2, pa3); BIAS(pB0, pB1, j); partialSM<DQK>(pB0, pB1, m_reg, mnB, alB);
.Lmy_h1B:
	s_waitcnt vmcnt(0)
	ds_write_b128 v146, v[88:91] offset:32768
	ds_write_b128 v145, v[92:95] offset:16384
	v_exp_f32_e32 v117, v114
	v_exp_f32_e32 v157, v115
	v_exp_f32_e32 v108, v108
	v_exp_f32_e32 v109, v109
	v_exp_f32_e32 v104, v104
	v_exp_f32_e32 v105, v105
	v_exp_f32_e32 v102, v102
	v_exp_f32_e32 v103, v103
	v_exp_f32_e32 v110, v110
	v_exp_f32_e32 v111, v111
	v_exp_f32_e32 v106, v106
	v_exp_f32_e32 v107, v107
	v_exp_f32_e32 v100, v100
	v_exp_f32_e32 v101, v101
	v_exp_f32_e32 v164, v112
	v_add_f32_e32 v112, 0, v126
	v_add_f32_e32 v112, v160, v112
	v_add_f32_e32 v112, v127, v112
	v_add_f32_e32 v112, v161, v112
	v_add_f32_e32 v112, v158, v112
	v_add_f32_e32 v112, v162, v112
	v_add_f32_e32 v112, v159, v112
	v_add_f32_e32 v112, v163, v112
	v_add_f32_e32 v112, v118, v112
	v_add_f32_e32 v112, v121, v112
	v_add_f32_e32 v112, v119, v112
	v_add_f32_e32 v112, v122, v112
	v_add_f32_e32 v112, v120, v112
	v_add_f32_e32 v112, v123, v112
	v_add_f32_e32 v112, v124, v112
	v_exp_f32_e32 v165, v113
	v_add_f32_e32 v112, v125, v112
	v_add_f32_e32 v112, v117, v112
	v_add_f32_e32 v112, v157, v112
	v_add_f32_e32 v112, v164, v112
	v_add_f32_e32 v112, v165, v112
	v_add_f32_e32 v112, v108, v112
	v_add_f32_e32 v112, v109, v112
	v_add_f32_e32 v112, v104, v112
	v_add_f32_e32 v112, v105, v112
	v_add_f32_e32 v112, v102, v112
	v_add_f32_e32 v112, v103, v112
	v_add_f32_e32 v112, v110, v112
	v_add_f32_e32 v112, v111, v112
	v_add_f32_e32 v112, v106, v112
	v_add_f32_e32 v112, v107, v112
	v_add_f32_e32 v112, v100, v112
	v_add_f32_e32 v155, v101, v112
	v_mov_b32_e32 v156, v155
	v_cvt_pk_bf16_f32 v214, v126, v160
	v_cvt_pk_bf16_f32 v215, v127, v161
	v_cvt_pk_bf16_f32 v216, v158, v162
	s_nop 1
	v_permlane32_swap_b32_e32 v155, v156
	v_cvt_pk_bf16_f32 v217, v159, v163
	v_permlane32_swap_b32_e32 v214, v216
	v_cvt_pk_bf16_f32 v218, v118, v121
	v_cvt_pk_bf16_f32 v219, v119, v122
	v_cvt_pk_bf16_f32 v220, v120, v123
	v_cvt_pk_bf16_f32 v221, v124, v125
	v_cvt_pk_bf16_f32 v222, v117, v157
	v_cvt_pk_bf16_f32 v223, v164, v165
	v_cvt_pk_bf16_f32 v224, v108, v109
	v_cvt_pk_bf16_f32 v225, v104, v105
	v_cvt_pk_bf16_f32 v226, v102, v103
	v_cvt_pk_bf16_f32 v227, v110, v111
	v_cvt_pk_bf16_f32 v228, v106, v107
	v_cvt_pk_bf16_f32 v229, v100, v101
	v_permlane32_swap_b32_e32 v215, v217
	v_permlane32_swap_b32_e32 v218, v220
	v_permlane32_swap_b32_e32 v219, v221
	v_permlane32_swap_b32_e32 v222, v224
	v_permlane32_swap_b32_e32 v223, v225
	v_permlane32_swap_b32_e32 v226, v228
	v_permlane32_swap_b32_e32 v227, v229
	s_cmpk_lt_u32 s25, 0x7e
	s_cselect_b32 s0, 0, 0xffffff80
	s_cselect_b32 s1, s10, s24
	s_add_i32 s0, s0, s11
	s_lshl_b32 s0, s0, 6
	s_add_i32 s0, s0, s1
	s_sub_i32 s0, s0, 64
	s_ashr_i32 s1, s0, 31
	s_cmpk_lt_u32 s25, 0x7f
	s_cselect_b32 s98, 0, 0xffffff80
	s_cselect_b32 s99, s10, s24
	s_add_i32 s98, s98, s11
	s_lshl_b32 s98, s98, 6
	s_add_i32 s98, s98, s99
	s_addk_i32 s98, 0xff80
	s_ashr_i32 s99, s98, 31
	v_lshl_add_u64 v[100:101], s[0:1], 0, v[130:131]
	v_lshl_add_u64 v[104:105], s[98:99], 0, v[130:131]
	v_lshlrev_b64 v[104:105], 9, v[104:105]
	v_lshl_add_u64 v[104:105], v[134:135], 0, v[104:105]
	v_mad_u64_u32 v[102:103], s[12:13], v100, s70, v[136:137]
	v_mad_i32_i24 v103, v101, s70, v103
	global_load_dwordx4 v[100:103], v[102:103], off
	s_nop 0
	global_load_dwordx4 v[108:111], v[104:105], off
	s_nop 0
	ds_read_b128 v[32:35], v148 offset:49152
	ds_read_b128 v[36:39], v148 offset:57344
	ds_read_b128 v[164:167], v152 offset:49152
	ds_read_b128 v[168:171], v152 offset:57344
	ds_read_b128 v[184:187], v151 offset:49152
	ds_read_b128 v[188:191], v151 offset:57344
	s_waitcnt lgkmcnt(5)
	v_mfma_f32_32x32x16_bf16 v[48:63], v[32:35], v[84:87], 0
	s_waitcnt lgkmcnt(4)
	v_mfma_f32_32x32x16_bf16 v[32:47], v[36:39], v[84:87], 0
	s_waitcnt lgkmcnt(3)
	v_mfma_f32_32x32x16_bf16 v[48:63], v[164:167], v[80:83], v[48:63]
	s_waitcnt lgkmcnt(2)
	v_mfma_f32_32x32x16_bf16 v[32:47], v[168:171], v[80:83], v[32:47]
	ds_read_b128 v[164:167], v149 offset:49152
	ds_read_b128 v[168:171], v149 offset:57344
	s_waitcnt lgkmcnt(3)
	v_mfma_f32_32x32x16_bf16 v[48:63], v[184:187], v[76:79], v[48:63]
	s_waitcnt lgkmcnt(2)
	v_mfma_f32_32x32x16_bf16 v[32:47], v[188:191], v[76:79], v[32:47]
	ds_read_b128 v[184:187], v150 offset:49152
	ds_read_b128 v[188:191], v150 offset:57344
	s_waitcnt lgkmcnt(3)
	v_mfma_f32_32x32x16_bf16 v[48:63], v[164:167], v[72:75], v[48:63]
	s_waitcnt lgkmcnt(2)
	v_mfma_f32_32x32x16_bf16 v[32:47], v[168:171], v[72:75], v[32:47]
	ds_read_b128 v[164:167], v153 offset:49152
	ds_read_b128 v[168:171], v153 offset:57344
	s_waitcnt lgkmcnt(3)
	v_mfma_f32_32x32x16_bf16 v[48:63], v[184:187], v[68:71], v[48:63]
	s_waitcnt lgkmcnt(2)
	v_mfma_f32_32x32x16_bf16 v[32:47], v[188:191], v[68:71], v[32:47]
	s_waitcnt lgkmcnt(1)
	v_mfma_f32_32x32x16_bf16 v[48:63], v[164:167], v[64:67], v[48:63]
	s_waitcnt lgkmcnt(0)
	v_mfma_f32_32x32x16_bf16 v[32:47], v[168:171], v[64:67], v[32:47]
	ds_read_b64_tr_b16 v[192:193], v144 offset:0
	ds_read_b64_tr_b16 v[194:195], v144 offset:0x800
	ds_read_b64_tr_b16 v[196:197], v144 offset:0x1000
	ds_read_b64_tr_b16 v[198:199], v144 offset:0x1800
	ds_read_b64_tr_b16 v[200:201], v144 offset:0x2000
	ds_read_b64_tr_b16 v[202:203], v144 offset:0x2800
	ds_read_b64_tr_b16 v[210:211], v144 offset:0x3000
	ds_read_b64_tr_b16 v[212:213], v144 offset:0x3800
	s_waitcnt lgkmcnt(0)
; #define SBAR() __builtin_amdgcn_sched_barrier(0)
; template <int DQK> __device__ __forceinline__ void partialSM(f32x16& p0, f32x16& p1, float& m_reg, float& mn, float& alpha) {
;   constexpr float SCALE = (DQK == 96) ? 0.10206207261596577f : 0.125f;
;   constexpr float C = SCALE * 1.4426950408889634f;
;   float pmax = p0[0];
; #pragma unroll
;   for (int r = 1; r < 16; ++r) pmax = fmaxf(pmax, p0[r]);
; #pragma unroll
;   for (int r = 0; r < 16; ++r) pmax = fmaxf(pmax, p1[r]);
;   { auto rr = __builtin_amdgcn_permlane32_swap(__float_as_uint(pmax), __float_as_uint(pmax), false, false);
;     pmax = fmaxf(__uint_as_float(rr[0]), __uint_as_float(rr[1])); }
;   if (__builtin_expect(__all(pmax - m_reg <= THR / SCALE), 1)) { mn = m_reg; alpha = 1.f; }
;   else { mn = fmaxf(m_reg, pmax); alpha = __builtin_amdgcn_exp2f((m_reg - mn) * C); m_reg = mn; }
;   float mnC = -mn * C;
; #pragma unroll
;   for (int r = 0; r < 16; ++r) p0[r] = fmaf(p0[r], C, mnC);
; #pragma unroll
;   for (int r = 0; r < 16; ++r) p1[r] = fmaf(p1[r], C, mnC);
; #pragma unroll
;   for (int r = 0; r < 16; ++r) p0[r] = __builtin_amdgcn_exp2f(p0[r]);
; }
; template <int D0> __device__ __forceinline__ void pv_one(f32x16& od, int vb, bf16x8 pa0, bf16x8 pa1, bf16x8 pa2, bf16x8 pa3) {
;   const s16x4 l0 = tr_read<v_rd_off(D0, 0, 0)>(vb), h0 = tr_read<v_rd_off(D0, 0, 1)>(vb), l1 = tr_read<v_rd_off(D0, 1, 0)>(vb), h1 = tr_read<v_rd_off(D0, 1, 1)>(vb);
;   const s16x4 l2 = tr_read<v_rd_off(D0, 2, 0)>(vb), h2 = tr_read<v_rd_off(D0, 2, 1)>(vb), l3 = tr_read<v_rd_off(D0, 3, 0)>(vb), h3 = tr_read<v_rd_off(D0, 3, 1)>(vb);
;   asm volatile("s_waitcnt lgkmcnt(0)" ::: "memory"); SBAR();
;   od = __builtin_amdgcn_mfma_f32_32x32x16_bf16(pa0, PKLH(l0, h0), od, 0, 0, 0);
;   od = __builtin_amdgcn_mfma_f32_32x32x16_bf16(pa1, PKLH(l1, h1), od, 0, 0, 0);
;   od = __builtin_amdgcn_mfma_f32_32x32x16_bf16(pa2, PKLH(l2, h2), od, 0, 0, 0);
;   od = __builtin_amdgcn_mfma_f32_32x32x16_bf16(pa3, PKLH(l3, h3), od, 0, 0, 0);
; }
; __device__ __forceinline__ void pv_d0(f32x16* o, int vb, bf16x8 pa0, bf16x8 pa1, bf16x8 pa2, bf16x8 pa3) {
;   pv_one<0>(o[0], vb, pa0, pa1, pa2, pa3); pv_one<1>(o[1], vb, pa0, pa1, pa2, pa3);
; }
	s_nop 0
	v_mfma_f32_32x32x16_bf16 v[0:15], v[214:217], v[192:195], v[0:15]
	ds_read_b64_tr_b16 v[192:193], v144 offset:0x200
	ds_read_b64_tr_b16 v[194:195], v144 offset:0xa00
	v_mfma_f32_32x32x16_bf16 v[0:15], v[218:221], v[196:199], v[0:15]
	ds_read_b64_tr_b16 v[196:197], v144 offset:0x1200
	ds_read_b64_tr_b16 v[198:199], v144 offset:0x1a00
	v_mfma_f32_32x32x16_bf16 v[0:15], v[222:225], v[200:203], v[0:15]
	ds_read_b64_tr_b16 v[200:201], v144 offset:0x2200
	ds_read_b64_tr_b16 v[202:203], v144 offset:0x2a00
	v_mfma_f32_32x32x16_bf16 v[0:15], v[226:229], v[210:213], v[0:15]
	ds_read_b64_tr_b16 v[210:211], v144 offset:0x3200
	ds_read_b64_tr_b16 v[212:213], v144 offset:0x3a00
	s_waitcnt lgkmcnt(0)
	v_mfma_f32_32x32x16_bf16 v[16:31], v[214:217], v[192:195], v[16:31]
	v_mfma_f32_32x32x16_bf16 v[16:31], v[218:221], v[196:199], v[16:31]
	v_mfma_f32_32x32x16_bf16 v[16:31], v[222:225], v[200:203], v[16:31]
	v_mfma_f32_32x32x16_bf16 v[16:31], v[226:229], v[210:213], v[16:31]
	v_max_f32_e32 v112, v48, v49
	v_max3_f32 v112, v112, v50, v51
	v_max3_f32 v112, v112, v52, v53
	v_max3_f32 v112, v112, v54, v55
	v_max3_f32 v112, v112, v56, v57
	v_max3_f32 v112, v112, v58, v59
	v_max3_f32 v112, v112, v60, v61
	v_max3_f32 v112, v112, v62, v63
	v_max3_f32 v112, v112, v32, v33
	v_max3_f32 v112, v112, v34, v35
	v_max3_f32 v112, v112, v36, v37
	v_max3_f32 v112, v112, v38, v39
	v_max3_f32 v112, v112, v40, v41
	v_max3_f32 v112, v112, v42, v43
	v_max3_f32 v112, v112, v44, v45
	v_max3_f32 v112, v112, v46, v47
	v_mov_b32_e32 v113, v112
	s_nop 1
	v_permlane32_swap_b32_e32 v112, v113
	v_max_f32_e32 v112, v112, v113
	v_sub_f32_e32 v113, v112, v116
	v_cmp_ge_f32_e32 vcc, s80, v113
	v_max_f32_e32 v112, v116, v112
	v_sub_f32_e32 v113, v116, v112
	v_mul_f32_e32 v113, 0x3e16c740, v113
	v_exp_f32_e32 v113, v113
	s_cmp_eq_u64 vcc, exec
	s_cselect_b64 s[0:1], -1, 0
	v_cndmask_b32_e64 v157, v113, 1.0, s[0:1]
	v_cmp_gt_f32_e32 vcc, 1.0, v157
	v_cndmask_b32_e64 v158, v112, v116, s[0:1]
	v_mul_f32_e32 v159, 0xbe16c740, v158
	v_fmamk_f32 v48, v48, 0x3e16c740, v159
	v_fmamk_f32 v49, v49, 0x3e16c740, v159
	v_fmamk_f32 v50, v50, 0x3e16c740, v159
	v_fmamk_f32 v51, v51, 0x3e16c740, v159
	v_fmamk_f32 v52, v52, 0x3e16c740, v159
	v_fmamk_f32 v53, v53, 0x3e16c740, v159
	v_fmamk_f32 v54, v54, 0x3e16c740, v159
	v_fmamk_f32 v55, v55, 0x3e16c740, v159
	v_fmamk_f32 v56, v56, 0x3e16c740, v159
	v_fmamk_f32 v57, v57, 0x3e16c740, v159
	v_fmamk_f32 v58, v58, 0x3e16c740, v159
	v_fmamk_f32 v59, v59, 0x3e16c740, v159
	v_fmamk_f32 v60, v60, 0x3e16c740, v159
	v_fmamk_f32 v61, v61, 0x3e16c740, v159
	v_fmamk_f32 v62, v62, 0x3e16c740, v159
	v_fmamk_f32 v63, v63, 0x3e16c740, v159
	v_exp_f32_e32 v112, v48
	v_exp_f32_e32 v127, v49
	v_exp_f32_e32 v113, v50
	v_exp_f32_e32 v126, v51
	v_exp_f32_e32 v114, v52
	v_exp_f32_e32 v125, v53
	v_exp_f32_e32 v115, v54
	v_exp_f32_e32 v124, v55
	v_exp_f32_e32 v116, v56
	v_exp_f32_e32 v123, v57
	v_exp_f32_e32 v117, v58
	v_exp_f32_e32 v122, v59
	v_exp_f32_e32 v118, v60
	v_exp_f32_e32 v121, v61
	v_exp_f32_e32 v119, v62
	v_exp_f32_e32 v120, v63
	v_fmamk_f32 v164, v42, 0x3e16c740, v159
	v_fmamk_f32 v165, v43, 0x3e16c740, v159
	v_fmamk_f32 v167, v32, 0x3e16c740, v159
	v_fmamk_f32 v168, v33, 0x3e16c740, v159
	v_fmamk_f32 v169, v34, 0x3e16c740, v159
	v_fmamk_f32 v170, v35, 0x3e16c740, v159
	v_fmamk_f32 v171, v36, 0x3e16c740, v159
	v_fmamk_f32 v172, v37, 0x3e16c740, v159
	v_fmamk_f32 v160, v38, 0x3e16c740, v159
	v_fmamk_f32 v161, v39, 0x3e16c740, v159
	v_fmamk_f32 v162, v40, 0x3e16c740, v159
	v_fmamk_f32 v163, v41, 0x3e16c740, v159
	v_fmamk_f32 v166, v44, 0x3e16c740, v159
	v_fmamk_f32 v173, v45, 0x3e16c740, v159
	v_fmamk_f32 v174, v46, 0x3e16c740, v159
	v_fmac_f32_e32 v159, 0x3e16c740, v47
	s_cbranch_vccz .Lmy_h1B_304
	s_and_saveexec_b64 s[12:13], s[4:5]
	ds_write_b32 v141, v157 offset:128
	s_or_b64 exec, exec, s[12:13]
	s_waitcnt lgkmcnt(0)
	ds_read_b128 v[192:195], v129 offset:224
	ds_read_b128 v[196:199], v129 offset:192
	ds_read_b128 v[200:203], v129 offset:160
	ds_read_b128 v[210:213], v129 offset:128
	s_waitcnt lgkmcnt(3)
	v_pk_mul_f32 v[14:15], v[14:15], v[194:195]
	s_waitcnt lgkmcnt(2)
	v_pk_mul_f32 v[10:11], v[10:11], v[198:199]
	s_waitcnt lgkmcnt(1)
	v_pk_mul_f32 v[6:7], v[6:7], v[202:203]
	s_waitcnt lgkmcnt(0)
	v_pk_mul_f32 v[2:3], v[2:3], v[212:213]
	v_pk_mul_f32 v[12:13], v[12:13], v[192:193]
	v_pk_mul_f32 v[8:9], v[8:9], v[196:197]
	v_pk_mul_f32 v[4:5], v[4:5], v[200:201]
	v_pk_mul_f32 v[0:1], v[0:1], v[210:211]
	v_pk_mul_f32 v[30:31], v[30:31], v[194:195]
	v_pk_mul_f32 v[26:27], v[26:27], v[198:199]
	v_pk_mul_f32 v[22:23], v[22:23], v[202:203]
	v_pk_mul_f32 v[18:19], v[18:19], v[212:213]
	v_pk_mul_f32 v[28:29], v[28:29], v[192:193]
	v_pk_mul_f32 v[24:25], v[24:25], v[196:197]
	v_pk_mul_f32 v[20:21], v[20:21], v[200:201]
	v_pk_mul_f32 v[16:17], v[16:17], v[210:211]
; #define SBAR() __builtin_amdgcn_sched_barrier(0)
; #define SLOAD(i, j) do { const long kr_ = KROW(j); sr_[i].vs0 = ld8(Vp + (kr_ + sr) * ldv + sc); sr_[i].ks0 = ld8(Kp + (kr_ + sr) * ldk + sc); \
;     if (DQK == 96) sr_[i].ks1 = ld8(Kp + (kr_ + sr2) * ldk + sc2); } while (0)
; #define SWRITE(b, i) do { *(bf16x8*)(V_lds + (b) * SHM_V + vst0) = sr_[i].vs0; *(bf16x8*)(K_lds + (b) * SHM_K + kst0) = sr_[i].ks0; \
;     if (DQK == 96) *(bf16x8*)(K_lds + (b) * SHM_K + kst1) = sr_[i].ks1; } while (0)
; #define RESC(a) do { if (__any((a) < 1.f)) { if (hi == 0) al_l[r32] = (a); asm volatile("s_waitcnt lgkmcnt(0)" ::: "memory"); \
;     _Pragma("unroll") for (int d = 0; d < 2; ++d) _Pragma("unroll") for (int r = 0; r < 16; ++r) o[d][r] *= al_l[crow(r, hi)]; } } while (0)
; __device__ __forceinline__ void finishSM(f32x16& p0, f32x16& p1, float alpha, float& l_reg, bf16x8& pa0, bf16x8& pa1, bf16x8& pa2, bf16x8& pa3) {
; #pragma unroll
;   for (int r = 0; r < 16; ++r) p1[r] = __builtin_amdgcn_exp2f(p1[r]);
;   float ps = 0;
; #pragma unroll
;   for (int r = 0; r < 16; ++r) ps += p0[r];
; #pragma unroll
;   for (int r = 0; r < 16; ++r) ps += p1[r];
;   { auto rr = __builtin_amdgcn_permlane32_swap(__float_as_uint(ps), __float_as_uint(ps), false, false);
;     ps = __uint_as_float(rr[0]) + __uint_as_float(rr[1]); }
;   l_reg = l_reg * alpha + ps;
;     ...
;   PK4(p0, 0, pa0); PK4(p0, 8, pa1); PK4(p1, 0, pa2); PK4(p1, 8, pa3);
;     ...
; }
; template <int DQK, int MODE, int ldq, int ldk, int ldv> ...
;     ...
;     __syncthreads(); SWRITE(0, SE);
;     RESC(alB); __syncthreads();
;     SBAR(); qkt<DQK>(pA0, pA1, K_lds, qr, r32, hi);
;     finishSM(pB0, pB1, alB, l_reg, pa0, pa1, pa2, pa3); SBAR();
;     if (j + 3 < NT) SLOAD(SE, j + 3); SBAR();
.Lmy_h1B_304:
	s_waitcnt lgkmcnt(0)
	s_barrier
	s_waitcnt vmcnt(0)
	ds_write_b128 v146, v[100:103] offset:49152
	ds_write_b128 v145, v[108:111]
	v_exp_f32_e32 v175, v164
	v_add_f32_e32 v164, 0, v112
	v_add_f32_e32 v164, v127, v164
	v_add_f32_e32 v164, v113, v164
	v_add_f32_e32 v164, v126, v164
	v_add_f32_e32 v164, v114, v164
	v_add_f32_e32 v164, v125, v164
	v_add_f32_e32 v164, v115, v164
	v_add_f32_e32 v164, v124, v164
	v_add_f32_e32 v164, v116, v164
	v_add_f32_e32 v164, v123, v164
	v_add_f32_e32 v164, v117, v164
	v_add_f32_e32 v164, v122, v164
	v_exp_f32_e32 v167, v167
	v_add_f32_e32 v164, v118, v164
	v_exp_f32_e32 v168, v168
	v_add_f32_e32 v164, v121, v164
	v_exp_f32_e32 v169, v169
	v_add_f32_e32 v164, v119, v164
	v_exp_f32_e32 v170, v170
	v_add_f32_e32 v164, v120, v164
	v_exp_f32_e32 v171, v171
	v_add_f32_e32 v164, v167, v164
	v_exp_f32_e32 v172, v172
	v_add_f32_e32 v164, v168, v164
	v_exp_f32_e32 v160, v160
	v_add_f32_e32 v164, v169, v164
	v_exp_f32_e32 v161, v161
	v_add_f32_e32 v164, v170, v164
	v_exp_f32_e32 v162, v162
	v_add_f32_e32 v164, v171, v164
	v_exp_f32_e32 v163, v163
	v_add_f32_e32 v164, v172, v164
	v_add_f32_e32 v164, v160, v164
	v_add_f32_e32 v164, v161, v164
	v_exp_f32_e32 v166, v166
	v_add_f32_e32 v164, v162, v164
	v_exp_f32_e32 v173, v173
	v_add_f32_e32 v164, v163, v164
	v_exp_f32_e32 v174, v174
	v_add_f32_e32 v164, v175, v164
	v_exp_f32_e32 v159, v159
	v_cvt_pk_bf16_f32 v214, v112, v127
	v_cvt_pk_bf16_f32 v215, v113, v126
	v_cvt_pk_bf16_f32 v216, v114, v125
	v_cvt_pk_bf16_f32 v217, v115, v124
	v_cvt_pk_bf16_f32 v218, v116, v123
	v_cvt_pk_bf16_f32 v219, v117, v122
	v_exp_f32_e32 v176, v165
	v_cvt_pk_bf16_f32 v220, v118, v121
	v_cvt_pk_bf16_f32 v221, v119, v120
	v_cvt_pk_bf16_f32 v222, v167, v168
	v_cvt_pk_bf16_f32 v223, v169, v170
	v_cvt_pk_bf16_f32 v224, v171, v172
	s_nop 0
	v_add_f32_e32 v164, v176, v164
	v_add_f32_e32 v164, v166, v164
	v_add_f32_e32 v164, v173, v164
	v_add_f32_e32 v164, v174, v164
	v_add_f32_e32 v164, v159, v164
	v_mov_b32_e32 v165, v164
	v_cvt_pk_bf16_f32 v225, v160, v161
	v_cvt_pk_bf16_f32 v226, v162, v163
	v_cvt_pk_bf16_f32 v227, v175, v176
	v_cvt_pk_bf16_f32 v228, v166, v173
	v_cvt_pk_bf16_f32 v229, v174, v159
	s_nop 1
	v_permlane32_swap_b32_e32 v164, v165
	v_permlane32_swap_b32_e32 v214, v216
	v_permlane32_swap_b32_e32 v215, v217
	v_permlane32_swap_b32_e32 v218, v220
	v_permlane32_swap_b32_e32 v219, v221
	v_permlane32_swap_b32_e32 v222, v224
	v_permlane32_swap_b32_e32 v223, v225
	v_permlane32_swap_b32_e32 v226, v228
	v_permlane32_swap_b32_e32 v227, v229
	s_cmpk_lt_u32 s25, 0x7e
	s_cselect_b32 s98, 0, 0xffffff80
	s_cselect_b32 s99, s10, s24
	s_add_i32 s98, s98, s11
	s_lshl_b32 s98, s98, 6
	s_add_i32 s98, s98, s99
	s_sub_i32 s98, s98, 64
	s_ashr_i32 s99, s98, 31
	v_lshl_add_u64 v[92:93], s[98:99], 0, v[130:131]
	v_lshlrev_b64 v[92:93], 9, v[92:93]
	v_lshl_add_u64 v[92:93], v[134:135], 0, v[92:93]
	global_load_dwordx4 v[92:95], v[92:93], off
	s_cmpk_gt_u32 s25, 0x80
	s_cbranch_scc1 .Lmy_h2B_306
	s_cmpk_lt_u32 s25, 0x7d
	s_cselect_b32 s0, 0, 0xffffff80
	s_cselect_b32 s1, s10, s24
	s_add_i32 s0, s0, s11
	s_lshl_b32 s0, s0, 6
	s_add_i32 s0, s0, s1
	s_ashr_i32 s1, s0, 31
	v_lshl_add_u64 v[88:89], s[0:1], 0, v[130:131]
	v_mad_u64_u32 v[90:91], s[12:13], v88, s70, v[136:137]
	v_mad_i32_i24 v91, v89, s70, v91
	global_load_dwordx4 v[88:91], v[90:91], off
	s_nop 0
	s_nop 0
; template <int DQK> __device__ __forceinline__ void partialSM(f32x16& p0, f32x16& p1, float& m_reg, float& mn, float& alpha) {
;   constexpr float SCALE = (DQK == 96) ? 0.10206207261596577f : 0.125f;
;   constexpr float C = SCALE * 1.4426950408889634f;
;   float pmax = p0[0];
; #pragma unroll
;   for (int r = 1; r < 16; ++r) pmax = fmaxf(pmax, p0[r]);
; #pragma unroll
;   for (int r = 0; r < 16; ++r) pmax = fmaxf(pmax, p1[r]);
;   { auto rr = __builtin_amdgcn_permlane32_swap(__float_as_uint(pmax), __float_as_uint(pmax), false, false);
;     pmax = fmaxf(__uint_as_float(rr[0]), __uint_as_float(rr[1])); }
;   if (__builtin_expect(__all(pmax - m_reg <= THR / SCALE), 1)) { mn = m_reg; alpha = 1.f; }
;   else { mn = fmaxf(m_reg, pmax); alpha = __builtin_amdgcn_exp2f((m_reg - mn) * C); m_reg = mn; }
;   float mnC = -mn * C;
; #pragma unroll
;   for (int r = 0; r < 16; ++r) p0[r] = fmaf(p0[r], C, mnC);
; #pragma unroll
;   for (int r = 0; r < 16; ++r) p1[r] = fmaf(p1[r], C, mnC);
; #pragma unroll
;   for (int r = 0; r < 16; ++r) p0[r] = __builtin_amdgcn_exp2f(p0[r]);
; }
; template <int DQK> __device__ __forceinline__ void qkt(f32x16& p0, f32x16& p1, const char* Ks, const bf16x8* qr, int r32, int hi) {
;   p0 = f32x16{}; p1 = f32x16{};
; #pragma unroll
;   for (int d0 = 0; d0 < DQK / 16; ++d0) { int cb = (d0 * 16 + hi * 8) * 2;
;     bf16x8 b0 = *reinterpret_cast<const bf16x8*>(Ks + KSWZ(r32, cb));
;     bf16x8 b1 = *reinterpret_cast<const bf16x8*>(Ks + KSWZ(32 + r32, cb));
;     p0 = __builtin_amdgcn_mfma_f32_32x32x16_bf16(b0, qr[d0], p0, 0, 0, 0);
;     p1 = __builtin_amdgcn_mfma_f32_32x32x16_bf16(b1, qr[d0], p1, 0, 0, 0); }
; }
; __device__ __forceinline__ int v_st(int k, int c) { const int kk = (k & ~0xC) | ((k & 4) << 1) | ((k & 8) >> 1); return ((kk >> 3) * 4 + (c >> 5)) * 512 + ((kk & 7) * 32 + (c & 31)) * 2; }
; __device__ __forceinline__ int v_rd_base(int lane) { return ((lane & 3) << 3) | (((lane >> 2) & 3) << 6) | (((lane >> 4) & 1) << 5) | (((lane >> 5) & 1) << 8); }
; template <int OFF> __device__ __forceinline__ s16x4 tr_read(int vb) {
;   s16x4 r; asm volatile("ds_read_b64_tr_b16 %0, %1 offset:%2" : "=&v"(r) : "v"(vb), "i"(OFF) : "memory"); return r;
; }
; template <int D0> __device__ __forceinline__ void pv_one(f32x16& od, int vb, bf16x8 pa0, bf16x8 pa1, bf16x8 pa2, bf16x8 pa3) {
.Lmy_h2B_306:
	ds_read_b128 v[32:35], v148 offset:32768
	ds_read_b128 v[36:39], v148 offset:40960
	ds_read_b128 v[176:179], v152 offset:32768
	ds_read_b128 v[180:183], v152 offset:40960
	ds_read_b128 v[184:187], v151 offset:32768
	ds_read_b128 v[188:191], v151 offset:40960
	s_waitcnt lgkmcnt(5)
	v_mfma_f32_32x32x16_bf16 v[48:63], v[32:35], v[84:87], 0
	s_waitcnt lgkmcnt(4)
	v_mfma_f32_32x32x16_bf16 v[32:47], v[36:39], v[84:87], 0
	s_waitcnt lgkmcnt(3)
	v_mfma_f32_32x32x16_bf16 v[48:63], v[176:179], v[80:83], v[48:63]
	s_waitcnt lgkmcnt(2)
	v_mfma_f32_32x32x16_bf16 v[32:47], v[180:183], v[80:83], v[32:47]
	ds_read_b128 v[176:179], v149 offset:32768
	ds_read_b128 v[180:183], v149 offset:40960
	s_waitcnt lgkmcnt(3)
	v_mfma_f32_32x32x16_bf16 v[48:63], v[184:187], v[76:79], v[48:63]
	s_waitcnt lgkmcnt(2)
	v_mfma_f32_32x32x16_bf16 v[32:47], v[188:191], v[76:79], v[32:47]
	ds_read_b128 v[184:187], v150 offset:32768
	ds_read_b128 v[188:191], v150 offset:40960
	s_waitcnt lgkmcnt(3)
	v_mfma_f32_32x32x16_bf16 v[48:63], v[176:179], v[72:75], v[48:63]
	s_waitcnt lgkmcnt(2)
	v_mfma_f32_32x32x16_bf16 v[32:47], v[180:183], v[72:75], v[32:47]
	ds_read_b128 v[176:179], v153 offset:32768
	ds_read_b128 v[180:183], v153 offset:40960
	s_waitcnt lgkmcnt(3)
	v_mfma_f32_32x32x16_bf16 v[48:63], v[184:187], v[68:71], v[48:63]
	s_waitcnt lgkmcnt(2)
	v_mfma_f32_32x32x16_bf16 v[32:47], v[188:191], v[68:71], v[32:47]
	s_waitcnt lgkmcnt(1)
	v_mfma_f32_32x32x16_bf16 v[48:63], v[176:179], v[64:67], v[48:63]
	s_waitcnt lgkmcnt(0)
	v_mfma_f32_32x32x16_bf16 v[32:47], v[180:183], v[64:67], v[32:47]
	ds_read_b64_tr_b16 v[192:193], v143 offset:0
	ds_read_b64_tr_b16 v[194:195], v143 offset:0x800
	ds_read_b64_tr_b16 v[196:197], v143 offset:0x1000
	ds_read_b64_tr_b16 v[198:199], v143 offset:0x1800
	ds_read_b64_tr_b16 v[200:201], v143 offset:0x2000
	ds_read_b64_tr_b16 v[202:203], v143 offset:0x2800
	ds_read_b64_tr_b16 v[210:211], v143 offset:0x3000
	ds_read_b64_tr_b16 v[212:213], v143 offset:0x3800
	s_waitcnt lgkmcnt(0)
	s_nop 0
	v_mfma_f32_32x32x16_bf16 v[0:15], v[214:217], v[192:195], v[0:15]
	ds_read_b64_tr_b16 v[192:193], v143 offset:0x200
	ds_read_b64_tr_b16 v[194:195], v143 offset:0xa00
	v_mfma_f32_32x32x16_bf16 v[0:15], v[218:221], v[196:199], v[0:15]
	ds_read_b64_tr_b16 v[196:197], v143 offset:0x1200
	ds_read_b64_tr_b16 v[198:199], v143 offset:0x1a00
	v_mfma_f32_32x32x16_bf16 v[0:15], v[222:225], v[200:203], v[0:15]
	ds_read_b64_tr_b16 v[200:201], v143 offset:0x2200
	ds_read_b64_tr_b16 v[202:203], v143 offset:0x2a00
	v_mfma_f32_32x32x16_bf16 v[0:15], v[226:229], v[210:213], v[0:15]
	ds_read_b64_tr_b16 v[210:211], v143 offset:0x3200
	ds_read_b64_tr_b16 v[212:213], v143 offset:0x3a00
	s_waitcnt lgkmcnt(0)
	v_mfma_f32_32x32x16_bf16 v[16:31], v[214:217], v[192:195], v[16:31]
	v_mfma_f32_32x32x16_bf16 v[16:31], v[218:221], v[196:199], v[16:31]
	v_mfma_f32_32x32x16_bf16 v[16:31], v[222:225], v[200:203], v[16:31]
	v_mfma_f32_32x32x16_bf16 v[16:31], v[226:229], v[210:213], v[16:31]
	v_max_f32_e32 v112, v48, v49
	v_max3_f32 v112, v112, v50, v51
	v_max3_f32 v112, v112, v52, v53
	v_max3_f32 v112, v112, v54, v55
	v_max3_f32 v112, v112, v56, v57
	v_max3_f32 v112, v112, v58, v59
	v_max3_f32 v112, v112, v60, v61
	v_max3_f32 v112, v112, v62, v63
	v_max3_f32 v112, v112, v32, v33
	v_max3_f32 v112, v112, v34, v35
	v_max3_f32 v112, v112, v36, v37
	v_max3_f32 v112, v112, v38, v39
	v_max3_f32 v112, v112, v40, v41
	v_max3_f32 v112, v112, v42, v43
	v_max3_f32 v112, v112, v44, v45
	v_max3_f32 v112, v112, v46, v47
	v_mov_b32_e32 v113, v112
	s_nop 1
	v_permlane32_swap_b32_e32 v112, v113
	v_max_f32_e32 v112, v112, v113
	v_sub_f32_e32 v113, v112, v158
	v_cmp_ge_f32_e32 vcc, s80, v113
	v_max_f32_e32 v112, v158, v112
	v_sub_f32_e32 v113, v158, v112
	v_mul_f32_e32 v113, 0x3e16c740, v113
	v_exp_f32_e32 v113, v113
	s_cmp_eq_u64 vcc, exec
	s_cselect_b64 s[0:1], -1, 0
	v_cndmask_b32_e64 v117, v113, 1.0, s[0:1]
	v_cmp_gt_f32_e32 vcc, 1.0, v117
	v_cndmask_b32_e64 v116, v112, v158, s[0:1]
	v_mul_f32_e32 v100, 0xbe16c740, v116
	v_mov_b32_e32 v101, v100
	v_fmamk_f32 v48, v48, 0x3e16c740, v100
	v_fmamk_f32 v49, v49, 0x3e16c740, v100
	v_fmamk_f32 v50, v50, 0x3e16c740, v100
	v_fmamk_f32 v51, v51, 0x3e16c740, v100
	v_fmamk_f32 v52, v52, 0x3e16c740, v100
	v_fmamk_f32 v53, v53, 0x3e16c740, v100
	v_fmamk_f32 v54, v54, 0x3e16c740, v100
	v_fmamk_f32 v55, v55, 0x3e16c740, v100
	v_fmamk_f32 v56, v56, 0x3e16c740, v100
	v_fmamk_f32 v57, v57, 0x3e16c740, v100
	v_fmamk_f32 v58, v58, 0x3e16c740, v100
	v_fmamk_f32 v59, v59, 0x3e16c740, v100
	v_fmamk_f32 v60, v60, 0x3e16c740, v100
	v_fmamk_f32 v61, v61, 0x3e16c740, v100
	v_fmamk_f32 v62, v62, 0x3e16c740, v100
	v_fmac_f32_e32 v101, 0x3e16c740, v63
	v_exp_f32_e32 v126, v48
	v_exp_f32_e32 v160, v49
	v_exp_f32_e32 v127, v50
	v_exp_f32_e32 v161, v51
	v_exp_f32_e32 v158, v52
	v_exp_f32_e32 v162, v53
	v_exp_f32_e32 v159, v54
	v_exp_f32_e32 v163, v55
	v_exp_f32_e32 v118, v56
	v_exp_f32_e32 v121, v57
	v_exp_f32_e32 v119, v58
	v_exp_f32_e32 v122, v59
	v_exp_f32_e32 v120, v60
	v_exp_f32_e32 v123, v61
	v_exp_f32_e32 v124, v62
	v_exp_f32_e32 v125, v101
	v_pk_fma_f32 v[114:115], v[32:33], s[40:41], v[100:101] op_sel_hi:[1,0,0]
	v_add_f32_e32 v32, v155, v156
	v_fmac_f32_e32 v32, v154, v142
	v_add_f32_e32 v142, v164, v165
	v_pk_fma_f32 v[112:113], v[34:35], s[40:41], v[100:101] op_sel_hi:[1,0,0]
	v_pk_fma_f32 v[108:109], v[36:37], s[40:41], v[100:101] op_sel_hi:[1,0,0]
	v_pk_fma_f32 v[104:105], v[38:39], s[40:41], v[100:101] op_sel_hi:[1,0,0]
	v_pk_fma_f32 v[102:103], v[40:41], s[40:41], v[100:101] op_sel_hi:[1,0,0]
	v_pk_fma_f32 v[110:111], v[42:43], s[40:41], v[100:101] op_sel_hi:[1,0,0]
	v_pk_fma_f32 v[106:107], v[44:45], s[40:41], v[100:101] op_sel_hi:[1,0,0]
	v_pk_fma_f32 v[100:101], v[46:47], s[40:41], v[100:101] op_sel_hi:[1,0,0]
	v_fmac_f32_e32 v142, v32, v157
	s_cbranch_vccz .Lmy_h2B_310
	s_and_saveexec_b64 s[12:13], s[4:5]
	ds_write_b32 v141, v117 offset:128
	s_or_b64 exec, exec, s[12:13]
	s_waitcnt lgkmcnt(0)
	ds_read_b128 v[192:195], v129 offset:224
	ds_read_b128 v[196:199], v129 offset:192
	ds_read_b128 v[200:203], v129 offset:160
	ds_read_b128 v[210:213], v129 offset:128
	s_waitcnt lgkmcnt(3)
	v_pk_mul_f32 v[14:15], v[14:15], v[194:195]
	s_waitcnt lgkmcnt(2)
	v_pk_mul_f32 v[10:11], v[10:11], v[198:199]
	s_waitcnt lgkmcnt(1)
	v_pk_mul_f32 v[6:7], v[6:7], v[202:203]
	s_waitcnt lgkmcnt(0)
	v_pk_mul_f32 v[2:3], v[2:3], v[212:213]
	v_pk_mul_f32 v[12:13], v[12:13], v[192:193]
	v_pk_mul_f32 v[8:9], v[8:9], v[196:197]
	v_pk_mul_f32 v[4:5], v[4:5], v[200:201]
	v_pk_mul_f32 v[0:1], v[0:1], v[210:211]
	v_pk_mul_f32 v[30:31], v[30:31], v[194:195]
	v_pk_mul_f32 v[26:27], v[26:27], v[198:199]
	v_pk_mul_f32 v[22:23], v[22:23], v[202:203]
	v_pk_mul_f32 v[18:19], v[18:19], v[212:213]
	v_pk_mul_f32 v[28:29], v[28:29], v[192:193]
	v_pk_mul_f32 v[24:25], v[24:25], v[196:197]
	v_pk_mul_f32 v[20:21], v[20:21], v[200:201]
	v_pk_mul_f32 v[16:17], v[16:17], v[210:211]
